# v34 + nt on the read-once f32 weight loads of the relocated weight conversion (mats 3-9)
# baseline (speedup 1.0000x reference)
.LBB0_2041:
	v_ashrrev_i32_e32 v4, 31, v51
	v_lshrrev_b32_e32 v4, 25, v4
	v_add_u32_e32 v4, v51, v4
	v_ashrrev_i32_e32 v4, 7, v4
	v_lshlrev_b32_e32 v9, 12, v4
	v_lshlrev_b32_e32 v8, 6, v4
	v_sub_u32_e32 v4, v52, v9
	v_add_u32_e32 v10, v4, v48
	v_lshrrev_b32_e32 v4, 1, v4
	v_and_b32_e32 v11, 0x7f, v10
	v_and_or_b32 v4, v4, s16, v11
	v_and_b32_e32 v11, 4, v51
	v_cmp_eq_u32_e32 vcc, 0, v11
	v_add_u32_e32 v12, 0x1c10, v4
	v_readlane_b32 s36, v238, 21
	v_cndmask_b32_e32 v11, v53, v54, vcc
	v_or_b32_e32 v11, v4, v11
	v_cndmask_b32_e32 v4, v12, v4, vcc
	v_cmp_gt_i32_e32 vcc, s12, v10
	v_readlane_b32 s42, v238, 27
	v_readlane_b32 s43, v238, 28
	v_cndmask_b32_e32 v4, v4, v11, vcc
	v_lshlrev_b32_e32 v4, 2, v4
	v_lshl_add_u64 v[38:39], s[42:43], 0, v[4:5]
	v_or_b32_e32 v34, v8, v1
	v_mov_b32_e32 v11, 0
	s_and_b64 vcc, exec, s[0:1]
	v_mov_b32_e32 v10, 0
	v_readlane_b32 s37, v238, 22
	v_readlane_b32 s38, v238, 23
	v_readlane_b32 s39, v238, 24
	v_readlane_b32 s40, v238, 25
	v_readlane_b32 s41, v238, 26
	v_readlane_b32 s44, v238, 29
	v_readlane_b32 s45, v238, 30
	v_readlane_b32 s46, v238, 31
	v_readlane_b32 s47, v238, 32
	v_readlane_b32 s48, v238, 33
	v_readlane_b32 s49, v238, 34
	v_readlane_b32 s50, v238, 35
	v_readlane_b32 s51, v238, 36
	s_cbranch_vccnz .LBB0_2043
	v_mad_i64_i32 v[12:13], s[22:23], v34, s17, v[38:39]
	global_load_dword v10, v[12:13], off nt
.LBB0_2043:
	s_and_b64 vcc, exec, s[0:1]
	s_cbranch_vccnz .LBB0_2045
	v_or_b32_e32 v4, 2, v34
	v_mad_i64_i32 v[12:13], s[22:23], v4, s17, v[38:39]
	global_load_dword v11, v[12:13], off nt
.LBB0_2045:
	v_mov_b32_e32 v13, 0
	s_and_b64 vcc, exec, s[0:1]
	v_mov_b32_e32 v12, 0
	s_cbranch_vccnz .LBB0_2047
	v_or_b32_e32 v4, 4, v34
	v_mad_i64_i32 v[14:15], s[22:23], v4, s17, v[38:39]
	global_load_dword v12, v[14:15], off nt
.LBB0_2047:
	s_and_b64 vcc, exec, s[0:1]
	s_cbranch_vccnz .LBB0_2049
	v_or_b32_e32 v4, 6, v34
	v_mad_i64_i32 v[14:15], s[22:23], v4, s17, v[38:39]
	global_load_dword v13, v[14:15], off nt
.LBB0_2049:
	v_mov_b32_e32 v15, 0
	s_and_b64 vcc, exec, s[0:1]
	v_mov_b32_e32 v14, 0
	s_cbranch_vccnz .LBB0_2051
	v_or_b32_e32 v4, 8, v34
	v_mad_i64_i32 v[16:17], s[22:23], v4, s17, v[38:39]
	global_load_dword v14, v[16:17], off nt
.LBB0_2051:
	s_and_b64 vcc, exec, s[0:1]
	s_cbranch_vccnz .LBB0_2053
	v_or_b32_e32 v4, 10, v34
	v_mad_i64_i32 v[16:17], s[22:23], v4, s17, v[38:39]
	global_load_dword v15, v[16:17], off nt
.LBB0_2053:
	v_mov_b32_e32 v17, 0
	s_and_b64 vcc, exec, s[0:1]
	v_mov_b32_e32 v16, 0
	s_cbranch_vccnz .LBB0_2055
	v_or_b32_e32 v4, 12, v34
	v_mad_i64_i32 v[18:19], s[22:23], v4, s17, v[38:39]
	global_load_dword v16, v[18:19], off nt
.LBB0_2055:
	s_and_b64 vcc, exec, s[0:1]
	s_cbranch_vccnz .LBB0_2057
	v_or_b32_e32 v4, 14, v34
	v_mad_i64_i32 v[18:19], s[22:23], v4, s17, v[38:39]
	global_load_dword v17, v[18:19], off nt
.LBB0_2057:
	v_mov_b32_e32 v19, 0
	s_and_b64 vcc, exec, s[0:1]
	v_mov_b32_e32 v18, 0
	s_cbranch_vccnz .LBB0_2059
	v_or_b32_e32 v4, 16, v34
	v_mad_i64_i32 v[20:21], s[22:23], v4, s17, v[38:39]
	global_load_dword v18, v[20:21], off nt
.LBB0_2059:
	s_and_b64 vcc, exec, s[0:1]
	s_cbranch_vccnz .LBB0_2061
	v_or_b32_e32 v4, 18, v34
	v_mad_i64_i32 v[20:21], s[22:23], v4, s17, v[38:39]
	global_load_dword v19, v[20:21], off nt
.LBB0_2061:
	v_mov_b32_e32 v21, 0
	s_and_b64 vcc, exec, s[0:1]
	v_mov_b32_e32 v20, 0
	s_cbranch_vccnz .LBB0_2063
	v_or_b32_e32 v4, 20, v34
	v_mad_i64_i32 v[22:23], s[22:23], v4, s17, v[38:39]
	global_load_dword v20, v[22:23], off nt
.LBB0_2063:
	s_and_b64 vcc, exec, s[0:1]
	s_cbranch_vccnz .LBB0_2065
	v_or_b32_e32 v4, 22, v34
	v_mad_i64_i32 v[22:23], s[22:23], v4, s17, v[38:39]
	global_load_dword v21, v[22:23], off nt
.LBB0_2065:
	v_mov_b32_e32 v23, 0
	s_and_b64 vcc, exec, s[0:1]
	v_mov_b32_e32 v22, 0
	s_cbranch_vccnz .LBB0_2067
	v_or_b32_e32 v4, 24, v34
	v_mad_i64_i32 v[24:25], s[22:23], v4, s17, v[38:39]
	global_load_dword v22, v[24:25], off nt
.LBB0_2067:
	s_and_b64 vcc, exec, s[0:1]
	s_cbranch_vccnz .LBB0_2069
	v_or_b32_e32 v4, 26, v34
	v_mad_i64_i32 v[24:25], s[22:23], v4, s17, v[38:39]
	global_load_dword v23, v[24:25], off nt
.LBB0_2069:
	v_mov_b32_e32 v25, 0
	s_and_b64 vcc, exec, s[0:1]
	v_mov_b32_e32 v24, 0
	s_cbranch_vccnz .LBB0_2071
	v_or_b32_e32 v4, 28, v34
	v_mad_i64_i32 v[26:27], s[22:23], v4, s17, v[38:39]
	global_load_dword v24, v[26:27], off nt
.LBB0_2071:
	s_and_b64 vcc, exec, s[0:1]
	s_cbranch_vccnz .LBB0_2073
	v_or_b32_e32 v4, 30, v34
	v_mad_i64_i32 v[26:27], s[22:23], v4, s17, v[38:39]
	global_load_dword v25, v[26:27], off nt
.LBB0_2073:
	v_mov_b32_e32 v27, 0
	s_and_b64 vcc, exec, s[0:1]
	v_mov_b32_e32 v26, 0
	s_cbranch_vccnz .LBB0_2075
	v_or_b32_e32 v4, 32, v34
	v_mad_i64_i32 v[28:29], s[22:23], v4, s17, v[38:39]
	global_load_dword v26, v[28:29], off nt
.LBB0_2075:
	s_and_b64 vcc, exec, s[0:1]
	s_cbranch_vccnz .LBB0_2077
	v_or_b32_e32 v4, 34, v34
	v_mad_i64_i32 v[28:29], s[22:23], v4, s17, v[38:39]
	global_load_dword v27, v[28:29], off nt
.LBB0_2077:
	v_mov_b32_e32 v29, 0
	s_and_b64 vcc, exec, s[0:1]
	v_mov_b32_e32 v28, 0
	s_cbranch_vccnz .LBB0_2079
	v_or_b32_e32 v4, 36, v34
	v_mad_i64_i32 v[30:31], s[22:23], v4, s17, v[38:39]
	global_load_dword v28, v[30:31], off nt
.LBB0_2079:
	s_and_b64 vcc, exec, s[0:1]
	s_cbranch_vccnz .LBB0_2081
	v_or_b32_e32 v4, 38, v34
	v_mad_i64_i32 v[30:31], s[22:23], v4, s17, v[38:39]
	global_load_dword v29, v[30:31], off nt
.LBB0_2081:
	v_mov_b32_e32 v31, 0
	s_and_b64 vcc, exec, s[0:1]
	v_mov_b32_e32 v30, 0
	s_cbranch_vccnz .LBB0_2083
	v_or_b32_e32 v4, 40, v34
	v_mad_i64_i32 v[32:33], s[22:23], v4, s17, v[38:39]
	global_load_dword v30, v[32:33], off nt
.LBB0_2083:
	s_and_b64 vcc, exec, s[0:1]
	s_cbranch_vccnz .LBB0_2085
	v_or_b32_e32 v4, 42, v34
	v_mad_i64_i32 v[32:33], s[22:23], v4, s17, v[38:39]
	global_load_dword v31, v[32:33], off nt
.LBB0_2085:
	v_mov_b32_e32 v33, 0
	s_and_b64 vcc, exec, s[0:1]
	v_mov_b32_e32 v32, 0
	s_cbranch_vccnz .LBB0_2087
	v_or_b32_e32 v4, 44, v34
	v_mad_i64_i32 v[36:37], s[22:23], v4, s17, v[38:39]
	global_load_dword v32, v[36:37], off nt
.LBB0_2087:
	s_and_b64 vcc, exec, s[0:1]
	s_cbranch_vccnz .LBB0_2089
	v_or_b32_e32 v4, 46, v34
	v_mad_i64_i32 v[36:37], s[22:23], v4, s17, v[38:39]
	global_load_dword v33, v[36:37], off nt
.LBB0_2089:
	v_mov_b32_e32 v37, 0
	s_and_b64 vcc, exec, s[0:1]
	v_mov_b32_e32 v36, 0
	s_cbranch_vccnz .LBB0_2091
	v_or_b32_e32 v4, 48, v34
	v_mad_i64_i32 v[40:41], s[22:23], v4, s17, v[38:39]
	global_load_dword v36, v[40:41], off nt
.LBB0_2091:
	s_and_b64 vcc, exec, s[0:1]
	s_cbranch_vccnz .LBB0_2093
	v_or_b32_e32 v4, 50, v34
	v_mad_i64_i32 v[40:41], s[22:23], v4, s17, v[38:39]
	global_load_dword v37, v[40:41], off nt
.LBB0_2093:
	v_mov_b32_e32 v41, 0
	s_and_b64 vcc, exec, s[0:1]
	v_mov_b32_e32 v40, 0
	s_cbranch_vccnz .LBB0_2095
	v_or_b32_e32 v4, 52, v34
	v_mad_i64_i32 v[42:43], s[22:23], v4, s17, v[38:39]
	global_load_dword v40, v[42:43], off nt
.LBB0_2095:
	s_and_b64 vcc, exec, s[0:1]
	s_cbranch_vccnz .LBB0_2097
	v_or_b32_e32 v4, 54, v34
	v_mad_i64_i32 v[42:43], s[22:23], v4, s17, v[38:39]
	global_load_dword v41, v[42:43], off nt
.LBB0_2097:
	v_mov_b32_e32 v43, 0
	s_and_b64 vcc, exec, s[0:1]
	v_mov_b32_e32 v42, 0
	s_cbranch_vccnz .LBB0_2099
	v_or_b32_e32 v4, 56, v34
	v_mad_i64_i32 v[44:45], s[22:23], v4, s17, v[38:39]
	global_load_dword v42, v[44:45], off nt
.LBB0_2099:
	s_and_b64 vcc, exec, s[0:1]
	s_cbranch_vccnz .LBB0_2101
	v_or_b32_e32 v4, 58, v34
	v_mad_i64_i32 v[44:45], s[22:23], v4, s17, v[38:39]
	global_load_dword v43, v[44:45], off nt
.LBB0_2101:
	v_mov_b32_e32 v45, 0
	s_and_b64 vcc, exec, s[0:1]
	v_mov_b32_e32 v44, 0
	s_cbranch_vccnz .LBB0_2103
	v_or_b32_e32 v4, 60, v34
	v_mad_i64_i32 v[56:57], s[22:23], v4, s17, v[38:39]
	global_load_dword v44, v[56:57], off nt
.LBB0_2103:
	s_and_b64 vcc, exec, s[0:1]
	s_cbranch_vccnz .LBB0_2105
	v_or_b32_e32 v4, 62, v34
	v_mad_i64_i32 v[38:39], s[22:23], v4, s17, v[38:39]
	global_load_dword v45, v[38:39], off nt
.LBB0_2105:
	s_andn2_b64 vcc, exec, s[8:9]
	s_cbranch_vccnz .LBB0_2040
	v_readlane_b32 s36, v238, 21
	v_ashrrev_i32_e32 v35, 31, v34
	v_readlane_b32 s40, v238, 25
	v_readlane_b32 s41, v238, 26
	v_readlane_b32 s37, v238, 22
	v_readlane_b32 s38, v238, 23
	v_lshl_add_u64 v[34:35], v[34:35], 2, s[40:41]
	global_load_dword v38, v[34:35], off nt
	global_load_dword v39, v[34:35], off offset:8
	global_load_dword v56, v[34:35], off offset:16
	global_load_dword v57, v[34:35], off offset:24
	global_load_dword v58, v[34:35], off offset:32
	global_load_dword v59, v[34:35], off offset:40
	global_load_dword v60, v[34:35], off offset:48
	global_load_dword v61, v[34:35], off offset:56
	global_load_dword v62, v[34:35], off offset:64
	global_load_dword v63, v[34:35], off offset:72
	global_load_dword v64, v[34:35], off offset:80
	global_load_dword v65, v[34:35], off offset:88
	global_load_dword v66, v[34:35], off offset:96
	global_load_dword v67, v[34:35], off offset:104
	global_load_dword v68, v[34:35], off offset:112
	global_load_dword v69, v[34:35], off offset:120
	global_load_dword v70, v[34:35], off offset:128
	global_load_dword v71, v[34:35], off offset:136
	global_load_dword v72, v[34:35], off offset:144
	global_load_dword v73, v[34:35], off offset:152
	global_load_dword v74, v[34:35], off offset:160
	global_load_dword v75, v[34:35], off offset:168
	global_load_dword v76, v[34:35], off offset:176
	global_load_dword v77, v[34:35], off offset:184
	global_load_dword v78, v[34:35], off offset:192
	global_load_dword v79, v[34:35], off offset:200
	global_load_dword v80, v[34:35], off offset:208
	global_load_dword v81, v[34:35], off offset:216
	global_load_dword v82, v[34:35], off offset:224
	global_load_dword v83, v[34:35], off offset:232
	global_load_dword v84, v[34:35], off offset:240
	global_load_dword v85, v[34:35], off offset:248
	v_readlane_b32 s39, v238, 24
	v_readlane_b32 s42, v238, 27
	v_readlane_b32 s43, v238, 28
	v_readlane_b32 s44, v238, 29
	v_readlane_b32 s45, v238, 30
	v_readlane_b32 s46, v238, 31
	v_readlane_b32 s47, v238, 32
	v_readlane_b32 s48, v238, 33
	v_readlane_b32 s49, v238, 34
	v_readlane_b32 s50, v238, 35
	v_readlane_b32 s51, v238, 36
	s_waitcnt vmcnt(30)
	v_pk_mul_f32 v[10:11], v[10:11], v[38:39]
	s_waitcnt vmcnt(28)
	v_pk_mul_f32 v[12:13], v[12:13], v[56:57]
	s_waitcnt vmcnt(26)
	v_pk_mul_f32 v[14:15], v[14:15], v[58:59]
	s_waitcnt vmcnt(24)
	v_pk_mul_f32 v[16:17], v[16:17], v[60:61]
	s_waitcnt vmcnt(22)
	v_pk_mul_f32 v[18:19], v[18:19], v[62:63]
	s_waitcnt vmcnt(20)
	v_pk_mul_f32 v[20:21], v[20:21], v[64:65]
	s_waitcnt vmcnt(18)
	v_pk_mul_f32 v[22:23], v[22:23], v[66:67]
	s_waitcnt vmcnt(16)
	v_pk_mul_f32 v[24:25], v[24:25], v[68:69]
	s_waitcnt vmcnt(14)
	v_pk_mul_f32 v[26:27], v[26:27], v[70:71]
	s_waitcnt vmcnt(12)
	v_pk_mul_f32 v[28:29], v[28:29], v[72:73]
	s_waitcnt vmcnt(10)
	v_pk_mul_f32 v[30:31], v[30:31], v[74:75]
	s_waitcnt vmcnt(8)
	v_pk_mul_f32 v[32:33], v[32:33], v[76:77]
	s_waitcnt vmcnt(6)
	v_pk_mul_f32 v[36:37], v[36:37], v[78:79]
	s_waitcnt vmcnt(4)
	v_pk_mul_f32 v[40:41], v[40:41], v[80:81]
	s_waitcnt vmcnt(2)
	v_pk_mul_f32 v[42:43], v[42:43], v[82:83]
	s_waitcnt vmcnt(0)
	v_pk_mul_f32 v[44:45], v[44:45], v[84:85]
	s_branch .LBB0_2040

.LBB0_2110:
	v_ashrrev_i32_e32 v6, 31, v44
	v_lshrrev_b32_e32 v6, 26, v6
	v_add_u32_e32 v6, v44, v6
	v_ashrrev_i32_e32 v8, 6, v6
	v_lshlrev_b32_e32 v7, 11, v8
	v_lshlrev_b32_e32 v8, 10, v8
	v_sub_u32_e32 v9, v45, v7
	v_sub_u32_e32 v8, v51, v8
	v_and_b32_e32 v8, 0xffffff80, v8
	v_and_b32_e32 v9, 0x60, v9
	v_or3_b32 v8, v9, v8, v48
	v_and_b32_e32 v9, 4, v44
	v_cmp_eq_u32_e32 vcc, 0, v9
	v_readlane_b32 s36, v238, 21
	v_and_b32_e32 v6, 0xffffffc0, v6
	v_cndmask_b32_e32 v9, v52, v53, vcc
	v_add_u32_e32 v8, v8, v9
	v_ashrrev_i32_e32 v9, 31, v8
	v_readlane_b32 s42, v238, 27
	v_readlane_b32 s43, v238, 28
	v_or_b32_e32 v32, v6, v1
	s_and_b64 vcc, exec, s[0:1]
	v_lshl_add_u64 v[36:37], v[8:9], 2, s[42:43]
	v_mov_b32_e32 v9, 0
	v_mov_b32_e32 v8, 0
	v_readlane_b32 s37, v238, 22
	v_readlane_b32 s38, v238, 23
	v_readlane_b32 s39, v238, 24
	v_readlane_b32 s40, v238, 25
	v_readlane_b32 s41, v238, 26
	v_readlane_b32 s44, v238, 29
	v_readlane_b32 s45, v238, 30
	v_readlane_b32 s46, v238, 31
	v_readlane_b32 s47, v238, 32
	v_readlane_b32 s48, v238, 33
	v_readlane_b32 s49, v238, 34
	v_readlane_b32 s50, v238, 35
	v_readlane_b32 s51, v238, 36
	s_cbranch_vccnz .LBB0_2112
	v_mad_i64_i32 v[10:11], s[18:19], v32, s16, v[36:37]
	global_load_dword v8, v[10:11], off nt
.LBB0_2112:
	s_and_b64 vcc, exec, s[0:1]
	s_cbranch_vccnz .LBB0_2114
	v_or_b32_e32 v9, 2, v32
	v_mad_i64_i32 v[10:11], s[18:19], v9, s16, v[36:37]
	global_load_dword v9, v[10:11], off nt
.LBB0_2114:
	v_mov_b32_e32 v11, 0
	s_and_b64 vcc, exec, s[0:1]
	v_mov_b32_e32 v10, 0
	s_cbranch_vccnz .LBB0_2116
	v_or_b32_e32 v10, 4, v32
	v_mad_i64_i32 v[12:13], s[18:19], v10, s16, v[36:37]
	global_load_dword v10, v[12:13], off nt
.LBB0_2116:
	s_and_b64 vcc, exec, s[0:1]
	s_cbranch_vccnz .LBB0_2118
	v_or_b32_e32 v11, 6, v32
	v_mad_i64_i32 v[12:13], s[18:19], v11, s16, v[36:37]
	global_load_dword v11, v[12:13], off nt
.LBB0_2118:
	v_mov_b32_e32 v13, 0
	s_and_b64 vcc, exec, s[0:1]
	v_mov_b32_e32 v12, 0
	s_cbranch_vccnz .LBB0_2120
	v_or_b32_e32 v12, 8, v32
	v_mad_i64_i32 v[14:15], s[18:19], v12, s16, v[36:37]
	global_load_dword v12, v[14:15], off nt
.LBB0_2120:
	s_and_b64 vcc, exec, s[0:1]
	s_cbranch_vccnz .LBB0_2122
	v_or_b32_e32 v13, 10, v32
	v_mad_i64_i32 v[14:15], s[18:19], v13, s16, v[36:37]
	global_load_dword v13, v[14:15], off nt
.LBB0_2122:
	v_mov_b32_e32 v15, 0
	s_and_b64 vcc, exec, s[0:1]
	v_mov_b32_e32 v14, 0
	s_cbranch_vccnz .LBB0_2124
	v_or_b32_e32 v14, 12, v32
	v_mad_i64_i32 v[16:17], s[18:19], v14, s16, v[36:37]
	global_load_dword v14, v[16:17], off nt
.LBB0_2124:
	s_and_b64 vcc, exec, s[0:1]
	s_cbranch_vccnz .LBB0_2126
	v_or_b32_e32 v15, 14, v32
	v_mad_i64_i32 v[16:17], s[18:19], v15, s16, v[36:37]
	global_load_dword v15, v[16:17], off nt
.LBB0_2126:
	v_mov_b32_e32 v17, 0
	s_and_b64 vcc, exec, s[0:1]
	v_mov_b32_e32 v16, 0
	s_cbranch_vccnz .LBB0_2128
	v_or_b32_e32 v16, 16, v32
	v_mad_i64_i32 v[18:19], s[18:19], v16, s16, v[36:37]
	global_load_dword v16, v[18:19], off nt
.LBB0_2128:
	s_and_b64 vcc, exec, s[0:1]
	s_cbranch_vccnz .LBB0_2130
	v_or_b32_e32 v17, 18, v32
	v_mad_i64_i32 v[18:19], s[18:19], v17, s16, v[36:37]
	global_load_dword v17, v[18:19], off nt
.LBB0_2130:
	v_mov_b32_e32 v19, 0
	s_and_b64 vcc, exec, s[0:1]
	v_mov_b32_e32 v18, 0
	s_cbranch_vccnz .LBB0_2132
	v_or_b32_e32 v18, 20, v32
	v_mad_i64_i32 v[20:21], s[18:19], v18, s16, v[36:37]
	global_load_dword v18, v[20:21], off nt
.LBB0_2132:
	s_and_b64 vcc, exec, s[0:1]
	s_cbranch_vccnz .LBB0_2134
	v_or_b32_e32 v19, 22, v32
	v_mad_i64_i32 v[20:21], s[18:19], v19, s16, v[36:37]
	global_load_dword v19, v[20:21], off nt
.LBB0_2134:
	v_mov_b32_e32 v21, 0
	s_and_b64 vcc, exec, s[0:1]
	v_mov_b32_e32 v20, 0
	s_cbranch_vccnz .LBB0_2136
	v_or_b32_e32 v20, 24, v32
	v_mad_i64_i32 v[22:23], s[18:19], v20, s16, v[36:37]
	global_load_dword v20, v[22:23], off nt
.LBB0_2136:
	s_and_b64 vcc, exec, s[0:1]
	s_cbranch_vccnz .LBB0_2138
	v_or_b32_e32 v21, 26, v32
	v_mad_i64_i32 v[22:23], s[18:19], v21, s16, v[36:37]
	global_load_dword v21, v[22:23], off nt
.LBB0_2138:
	v_mov_b32_e32 v23, 0
	s_and_b64 vcc, exec, s[0:1]
	v_mov_b32_e32 v22, 0
	s_cbranch_vccnz .LBB0_2140
	v_or_b32_e32 v22, 28, v32
	v_mad_i64_i32 v[24:25], s[18:19], v22, s16, v[36:37]
	global_load_dword v22, v[24:25], off nt
.LBB0_2140:
	s_and_b64 vcc, exec, s[0:1]
	s_cbranch_vccnz .LBB0_2142
	v_or_b32_e32 v23, 30, v32
	v_mad_i64_i32 v[24:25], s[18:19], v23, s16, v[36:37]
	global_load_dword v23, v[24:25], off nt
.LBB0_2142:
	v_mov_b32_e32 v25, 0
	s_and_b64 vcc, exec, s[0:1]
	v_mov_b32_e32 v24, 0
	s_cbranch_vccnz .LBB0_2144
	v_or_b32_e32 v24, 32, v32
	v_mad_i64_i32 v[26:27], s[18:19], v24, s16, v[36:37]
	global_load_dword v24, v[26:27], off nt
.LBB0_2144:
	s_and_b64 vcc, exec, s[0:1]
	s_cbranch_vccnz .LBB0_2146
	v_or_b32_e32 v25, 34, v32
	v_mad_i64_i32 v[26:27], s[18:19], v25, s16, v[36:37]
	global_load_dword v25, v[26:27], off nt
.LBB0_2146:
	v_mov_b32_e32 v27, 0
	s_and_b64 vcc, exec, s[0:1]
	v_mov_b32_e32 v26, 0
	s_cbranch_vccnz .LBB0_2148
	v_or_b32_e32 v26, 36, v32
	v_mad_i64_i32 v[28:29], s[18:19], v26, s16, v[36:37]
	global_load_dword v26, v[28:29], off nt
.LBB0_2148:
	s_and_b64 vcc, exec, s[0:1]
	s_cbranch_vccnz .LBB0_2150
	v_or_b32_e32 v27, 38, v32
	v_mad_i64_i32 v[28:29], s[18:19], v27, s16, v[36:37]
	global_load_dword v27, v[28:29], off nt
.LBB0_2150:
	v_mov_b32_e32 v29, 0
	s_and_b64 vcc, exec, s[0:1]
	v_mov_b32_e32 v28, 0
	s_cbranch_vccnz .LBB0_2152
	v_or_b32_e32 v28, 40, v32
	v_mad_i64_i32 v[30:31], s[18:19], v28, s16, v[36:37]
	global_load_dword v28, v[30:31], off nt
.LBB0_2152:
	s_and_b64 vcc, exec, s[0:1]
	s_cbranch_vccnz .LBB0_2154
	v_or_b32_e32 v29, 42, v32
	v_mad_i64_i32 v[30:31], s[18:19], v29, s16, v[36:37]
	global_load_dword v29, v[30:31], off nt
.LBB0_2154:
	v_mov_b32_e32 v31, 0
	s_and_b64 vcc, exec, s[0:1]
	v_mov_b32_e32 v30, 0
	s_cbranch_vccnz .LBB0_2156
	v_or_b32_e32 v30, 44, v32
	v_mad_i64_i32 v[34:35], s[18:19], v30, s16, v[36:37]
	global_load_dword v30, v[34:35], off nt
.LBB0_2156:
	s_and_b64 vcc, exec, s[0:1]
	s_cbranch_vccnz .LBB0_2158
	v_or_b32_e32 v31, 46, v32
	v_mad_i64_i32 v[34:35], s[18:19], v31, s16, v[36:37]
	global_load_dword v31, v[34:35], off nt
.LBB0_2158:
	v_mov_b32_e32 v35, 0
	s_and_b64 vcc, exec, s[0:1]
	v_mov_b32_e32 v34, 0
	s_cbranch_vccnz .LBB0_2160
	v_or_b32_e32 v33, 48, v32
	v_mad_i64_i32 v[38:39], s[18:19], v33, s16, v[36:37]
	global_load_dword v34, v[38:39], off nt
.LBB0_2160:
	s_and_b64 vcc, exec, s[0:1]
	s_cbranch_vccnz .LBB0_2162
	v_or_b32_e32 v33, 50, v32
	v_mad_i64_i32 v[38:39], s[18:19], v33, s16, v[36:37]
	global_load_dword v35, v[38:39], off nt
.LBB0_2162:
	v_mov_b32_e32 v39, 0
	s_and_b64 vcc, exec, s[0:1]
	v_mov_b32_e32 v38, 0
	s_cbranch_vccnz .LBB0_2164
	v_or_b32_e32 v33, 52, v32
	v_mad_i64_i32 v[40:41], s[18:19], v33, s16, v[36:37]
	global_load_dword v38, v[40:41], off nt
.LBB0_2164:
	s_and_b64 vcc, exec, s[0:1]
	s_cbranch_vccnz .LBB0_2166
	v_or_b32_e32 v33, 54, v32
	v_mad_i64_i32 v[40:41], s[18:19], v33, s16, v[36:37]
	global_load_dword v39, v[40:41], off nt
.LBB0_2166:
	v_mov_b32_e32 v41, 0
	s_and_b64 vcc, exec, s[0:1]
	v_mov_b32_e32 v40, 0
	s_cbranch_vccnz .LBB0_2168
	v_or_b32_e32 v33, 56, v32
	v_mad_i64_i32 v[42:43], s[18:19], v33, s16, v[36:37]
	global_load_dword v40, v[42:43], off nt
.LBB0_2168:
	s_and_b64 vcc, exec, s[0:1]
	s_cbranch_vccnz .LBB0_2170
	v_or_b32_e32 v33, 58, v32
	v_mad_i64_i32 v[42:43], s[18:19], v33, s16, v[36:37]
	global_load_dword v41, v[42:43], off nt
.LBB0_2170:
	v_mov_b32_e32 v43, 0
	s_and_b64 vcc, exec, s[0:1]
	v_mov_b32_e32 v42, 0
	s_cbranch_vccnz .LBB0_2172
	v_or_b32_e32 v33, 60, v32
	v_mad_i64_i32 v[54:55], s[18:19], v33, s16, v[36:37]
	global_load_dword v42, v[54:55], off nt
.LBB0_2172:
	s_and_b64 vcc, exec, s[0:1]
	s_cbranch_vccnz .LBB0_2174
	v_or_b32_e32 v33, 62, v32
	v_mad_i64_i32 v[36:37], s[18:19], v33, s16, v[36:37]
	global_load_dword v43, v[36:37], off nt
.LBB0_2174:
	s_andn2_b64 vcc, exec, s[8:9]
	s_cbranch_vccnz .LBB0_2109
	v_readlane_b32 s36, v238, 21
	v_ashrrev_i32_e32 v33, 31, v32
	v_readlane_b32 s40, v238, 25
	v_readlane_b32 s41, v238, 26
	v_readlane_b32 s37, v238, 22
	v_readlane_b32 s38, v238, 23
	v_lshl_add_u64 v[32:33], v[32:33], 2, s[40:41]
	global_load_dword v36, v[32:33], off nt
	global_load_dword v37, v[32:33], off offset:8
	global_load_dword v54, v[32:33], off offset:16
	global_load_dword v55, v[32:33], off offset:24
	global_load_dword v56, v[32:33], off offset:32
	global_load_dword v57, v[32:33], off offset:40
	global_load_dword v58, v[32:33], off offset:48
	global_load_dword v59, v[32:33], off offset:56
	global_load_dword v60, v[32:33], off offset:64
	global_load_dword v61, v[32:33], off offset:72
	global_load_dword v62, v[32:33], off offset:80
	global_load_dword v63, v[32:33], off offset:88
	global_load_dword v64, v[32:33], off offset:96
	global_load_dword v65, v[32:33], off offset:104
	global_load_dword v66, v[32:33], off offset:112
	global_load_dword v67, v[32:33], off offset:120
	global_load_dword v68, v[32:33], off offset:128
	global_load_dword v69, v[32:33], off offset:136
	global_load_dword v70, v[32:33], off offset:144
	global_load_dword v71, v[32:33], off offset:152
	global_load_dword v72, v[32:33], off offset:160
	global_load_dword v73, v[32:33], off offset:168
	global_load_dword v74, v[32:33], off offset:176
	global_load_dword v75, v[32:33], off offset:184
	global_load_dword v76, v[32:33], off offset:192
	global_load_dword v77, v[32:33], off offset:200
	global_load_dword v78, v[32:33], off offset:208
	global_load_dword v79, v[32:33], off offset:216
	global_load_dword v80, v[32:33], off offset:224
	global_load_dword v81, v[32:33], off offset:232
	global_load_dword v82, v[32:33], off offset:240
	global_load_dword v83, v[32:33], off offset:248
	v_readlane_b32 s39, v238, 24
	v_readlane_b32 s42, v238, 27
	v_readlane_b32 s43, v238, 28
	v_readlane_b32 s44, v238, 29
	v_readlane_b32 s45, v238, 30
	v_readlane_b32 s46, v238, 31
	v_readlane_b32 s47, v238, 32
	v_readlane_b32 s48, v238, 33
	v_readlane_b32 s49, v238, 34
	v_readlane_b32 s50, v238, 35
	v_readlane_b32 s51, v238, 36
	s_waitcnt vmcnt(30)
	v_pk_mul_f32 v[8:9], v[8:9], v[36:37]
	s_waitcnt vmcnt(28)
	v_pk_mul_f32 v[10:11], v[10:11], v[54:55]
	s_waitcnt vmcnt(26)
	v_pk_mul_f32 v[12:13], v[12:13], v[56:57]
	s_waitcnt vmcnt(24)
	v_pk_mul_f32 v[14:15], v[14:15], v[58:59]
	s_waitcnt vmcnt(22)
	v_pk_mul_f32 v[16:17], v[16:17], v[60:61]
	s_waitcnt vmcnt(20)
	v_pk_mul_f32 v[18:19], v[18:19], v[62:63]
	s_waitcnt vmcnt(18)
	v_pk_mul_f32 v[20:21], v[20:21], v[64:65]
	s_waitcnt vmcnt(16)
	v_pk_mul_f32 v[22:23], v[22:23], v[66:67]
	s_waitcnt vmcnt(14)
	v_pk_mul_f32 v[24:25], v[24:25], v[68:69]
	s_waitcnt vmcnt(12)
	v_pk_mul_f32 v[26:27], v[26:27], v[70:71]
	s_waitcnt vmcnt(10)
	v_pk_mul_f32 v[28:29], v[28:29], v[72:73]
	s_waitcnt vmcnt(8)
	v_pk_mul_f32 v[30:31], v[30:31], v[74:75]
	s_waitcnt vmcnt(6)
	v_pk_mul_f32 v[34:35], v[34:35], v[76:77]
	s_waitcnt vmcnt(4)
	v_pk_mul_f32 v[38:39], v[38:39], v[78:79]
	s_waitcnt vmcnt(2)
	v_pk_mul_f32 v[40:41], v[40:41], v[80:81]
	s_waitcnt vmcnt(0)
	v_pk_mul_f32 v[42:43], v[42:43], v[82:83]
	s_branch .LBB0_2109

.LBB0_2179:
	v_ashrrev_i32_e32 v6, 31, v12
	v_lshrrev_b32_e32 v6, 27, v6
	v_add_u32_e32 v6, v12, v6
	v_ashrrev_i32_e32 v7, 5, v6
	v_lshlrev_b32_e32 v6, 6, v7
	v_lshlrev_b32_e32 v7, 10, v7
	v_add_u32_e32 v8, v48, v13
	v_sub_u32_e32 v8, v8, v7
	v_readlane_b32 s36, v238, 37
	v_ashrrev_i32_e32 v9, 31, v8
	v_readlane_b32 s38, v238, 39
	v_readlane_b32 s39, v238, 40
	v_or_b32_e32 v10, v6, v1
	v_mov_b32_e32 v14, 0
	v_lshl_add_u64 v[8:9], v[8:9], 2, s[38:39]
	s_and_b64 vcc, exec, s[0:1]
	v_mov_b32_e32 v11, 0
	v_readlane_b32 s37, v238, 38
	v_readlane_b32 s40, v238, 41
	v_readlane_b32 s41, v238, 42
	v_readlane_b32 s42, v238, 43
	v_readlane_b32 s43, v238, 44
	v_readlane_b32 s44, v238, 45
	v_readlane_b32 s45, v238, 46
	v_readlane_b32 s46, v238, 47
	v_readlane_b32 s47, v238, 48
	v_readlane_b32 s48, v238, 49
	v_readlane_b32 s49, v238, 50
	v_readlane_b32 s50, v238, 51
	v_readlane_b32 s51, v238, 52
	s_cbranch_vccnz .LBB0_2181
	v_ashrrev_i32_e32 v11, 31, v10
	v_lshlrev_b64 v[16:17], 12, v[10:11]
	v_lshl_add_u64 v[16:17], v[8:9], 0, v[16:17]
	global_load_dword v11, v[16:17], off nt
.LBB0_2181:
	s_and_b64 vcc, exec, s[0:1]
	s_cbranch_vccnz .LBB0_2183
	v_or_b32_e32 v14, 2, v10
	v_ashrrev_i32_e32 v15, 31, v14
	v_lshlrev_b64 v[14:15], 12, v[14:15]
	v_lshl_add_u64 v[14:15], v[8:9], 0, v[14:15]
	global_load_dword v14, v[14:15], off nt
.LBB0_2183:
	v_mov_b32_e32 v15, 0
	s_and_b64 vcc, exec, s[0:1]
	v_mov_b32_e32 v16, 0
	s_cbranch_vccnz .LBB0_2185
	v_or_b32_e32 v16, 4, v10
	v_ashrrev_i32_e32 v17, 31, v16
	v_lshlrev_b64 v[16:17], 12, v[16:17]
	v_lshl_add_u64 v[16:17], v[8:9], 0, v[16:17]
	global_load_dword v16, v[16:17], off nt
.LBB0_2185:
	s_and_b64 vcc, exec, s[0:1]
	s_cbranch_vccnz .LBB0_2187
	v_or_b32_e32 v18, 6, v10
	v_ashrrev_i32_e32 v19, 31, v18
	v_lshlrev_b64 v[18:19], 12, v[18:19]
	v_lshl_add_u64 v[18:19], v[8:9], 0, v[18:19]
	global_load_dword v15, v[18:19], off nt
.LBB0_2187:
	v_mov_b32_e32 v17, 0
	s_and_b64 vcc, exec, s[0:1]
	v_mov_b32_e32 v18, 0
	s_cbranch_vccnz .LBB0_2189
	v_or_b32_e32 v18, 8, v10
	v_ashrrev_i32_e32 v19, 31, v18
	v_lshlrev_b64 v[18:19], 12, v[18:19]
	v_lshl_add_u64 v[18:19], v[8:9], 0, v[18:19]
	global_load_dword v18, v[18:19], off nt
.LBB0_2189:
	s_and_b64 vcc, exec, s[0:1]
	s_cbranch_vccnz .LBB0_2191
	v_or_b32_e32 v20, 10, v10
	v_ashrrev_i32_e32 v21, 31, v20
	v_lshlrev_b64 v[20:21], 12, v[20:21]
	v_lshl_add_u64 v[20:21], v[8:9], 0, v[20:21]
	global_load_dword v17, v[20:21], off nt
.LBB0_2191:
	v_mov_b32_e32 v19, 0
	s_and_b64 vcc, exec, s[0:1]
	v_mov_b32_e32 v20, 0
	s_cbranch_vccnz .LBB0_2193
	v_or_b32_e32 v20, 12, v10
	v_ashrrev_i32_e32 v21, 31, v20
	v_lshlrev_b64 v[20:21], 12, v[20:21]
	v_lshl_add_u64 v[20:21], v[8:9], 0, v[20:21]
	global_load_dword v20, v[20:21], off nt
.LBB0_2193:
	s_and_b64 vcc, exec, s[0:1]
	s_cbranch_vccnz .LBB0_2195
	v_or_b32_e32 v22, 14, v10
	v_ashrrev_i32_e32 v23, 31, v22
	v_lshlrev_b64 v[22:23], 12, v[22:23]
	v_lshl_add_u64 v[22:23], v[8:9], 0, v[22:23]
	global_load_dword v19, v[22:23], off nt
.LBB0_2195:
	v_mov_b32_e32 v21, 0
	s_and_b64 vcc, exec, s[0:1]
	v_mov_b32_e32 v22, 0
	s_cbranch_vccnz .LBB0_2197
	v_or_b32_e32 v22, 16, v10
	v_ashrrev_i32_e32 v23, 31, v22
	v_lshlrev_b64 v[22:23], 12, v[22:23]
	v_lshl_add_u64 v[22:23], v[8:9], 0, v[22:23]
	global_load_dword v22, v[22:23], off nt
.LBB0_2197:
	s_and_b64 vcc, exec, s[0:1]
	s_cbranch_vccnz .LBB0_2199
	v_or_b32_e32 v24, 18, v10
	v_ashrrev_i32_e32 v25, 31, v24
	v_lshlrev_b64 v[24:25], 12, v[24:25]
	v_lshl_add_u64 v[24:25], v[8:9], 0, v[24:25]
	global_load_dword v21, v[24:25], off nt
.LBB0_2199:
	v_mov_b32_e32 v23, 0
	s_and_b64 vcc, exec, s[0:1]
	v_mov_b32_e32 v24, 0
	s_cbranch_vccnz .LBB0_2201
	v_or_b32_e32 v24, 20, v10
	v_ashrrev_i32_e32 v25, 31, v24
	v_lshlrev_b64 v[24:25], 12, v[24:25]
	v_lshl_add_u64 v[24:25], v[8:9], 0, v[24:25]
	global_load_dword v24, v[24:25], off nt
.LBB0_2201:
	s_and_b64 vcc, exec, s[0:1]
	s_cbranch_vccnz .LBB0_2203
	v_or_b32_e32 v26, 22, v10
	v_ashrrev_i32_e32 v27, 31, v26
	v_lshlrev_b64 v[26:27], 12, v[26:27]
	v_lshl_add_u64 v[26:27], v[8:9], 0, v[26:27]
	global_load_dword v23, v[26:27], off nt
.LBB0_2203:
	v_mov_b32_e32 v25, 0
	s_and_b64 vcc, exec, s[0:1]
	v_mov_b32_e32 v26, 0
	s_cbranch_vccnz .LBB0_2205
	v_or_b32_e32 v26, 24, v10
	v_ashrrev_i32_e32 v27, 31, v26
	v_lshlrev_b64 v[26:27], 12, v[26:27]
	v_lshl_add_u64 v[26:27], v[8:9], 0, v[26:27]
	global_load_dword v26, v[26:27], off nt
.LBB0_2205:
	s_and_b64 vcc, exec, s[0:1]
	s_cbranch_vccnz .LBB0_2207
	v_or_b32_e32 v28, 26, v10
	v_ashrrev_i32_e32 v29, 31, v28
	v_lshlrev_b64 v[28:29], 12, v[28:29]
	v_lshl_add_u64 v[28:29], v[8:9], 0, v[28:29]
	global_load_dword v25, v[28:29], off nt
.LBB0_2207:
	v_mov_b32_e32 v27, 0
	s_and_b64 vcc, exec, s[0:1]
	v_mov_b32_e32 v28, 0
	s_cbranch_vccnz .LBB0_2209
	v_or_b32_e32 v28, 28, v10
	v_ashrrev_i32_e32 v29, 31, v28
	v_lshlrev_b64 v[28:29], 12, v[28:29]
	v_lshl_add_u64 v[28:29], v[8:9], 0, v[28:29]
	global_load_dword v28, v[28:29], off nt
.LBB0_2209:
	s_and_b64 vcc, exec, s[0:1]
	s_cbranch_vccnz .LBB0_2211
	v_or_b32_e32 v30, 30, v10
	v_ashrrev_i32_e32 v31, 31, v30
	v_lshlrev_b64 v[30:31], 12, v[30:31]
	v_lshl_add_u64 v[30:31], v[8:9], 0, v[30:31]
	global_load_dword v27, v[30:31], off nt
.LBB0_2211:
	v_mov_b32_e32 v29, 0
	s_and_b64 vcc, exec, s[0:1]
	v_mov_b32_e32 v30, 0
	s_cbranch_vccnz .LBB0_2213
	v_or_b32_e32 v30, 32, v10
	v_ashrrev_i32_e32 v31, 31, v30
	v_lshlrev_b64 v[30:31], 12, v[30:31]
	v_lshl_add_u64 v[30:31], v[8:9], 0, v[30:31]
	global_load_dword v30, v[30:31], off nt
.LBB0_2213:
	s_and_b64 vcc, exec, s[0:1]
	s_cbranch_vccnz .LBB0_2215
	v_or_b32_e32 v32, 34, v10
	v_ashrrev_i32_e32 v33, 31, v32
	v_lshlrev_b64 v[32:33], 12, v[32:33]
	v_lshl_add_u64 v[32:33], v[8:9], 0, v[32:33]
	global_load_dword v29, v[32:33], off nt
.LBB0_2215:
	v_mov_b32_e32 v31, 0
	s_and_b64 vcc, exec, s[0:1]
	v_mov_b32_e32 v32, 0
	s_cbranch_vccnz .LBB0_2217
	v_or_b32_e32 v32, 36, v10
	v_ashrrev_i32_e32 v33, 31, v32
	v_lshlrev_b64 v[32:33], 12, v[32:33]
	v_lshl_add_u64 v[32:33], v[8:9], 0, v[32:33]
	global_load_dword v32, v[32:33], off nt
.LBB0_2217:
	s_and_b64 vcc, exec, s[0:1]
	s_cbranch_vccnz .LBB0_2219
	v_or_b32_e32 v34, 38, v10
	v_ashrrev_i32_e32 v35, 31, v34
	v_lshlrev_b64 v[34:35], 12, v[34:35]
	v_lshl_add_u64 v[34:35], v[8:9], 0, v[34:35]
	global_load_dword v31, v[34:35], off nt
.LBB0_2219:
	v_mov_b32_e32 v33, 0
	s_and_b64 vcc, exec, s[0:1]
	v_mov_b32_e32 v34, 0
	s_cbranch_vccnz .LBB0_2221
	v_or_b32_e32 v34, 40, v10
	v_ashrrev_i32_e32 v35, 31, v34
	v_lshlrev_b64 v[34:35], 12, v[34:35]
	v_lshl_add_u64 v[34:35], v[8:9], 0, v[34:35]
	global_load_dword v34, v[34:35], off nt
.LBB0_2221:
	s_and_b64 vcc, exec, s[0:1]
	s_cbranch_vccnz .LBB0_2223
	v_or_b32_e32 v36, 42, v10
	v_ashrrev_i32_e32 v37, 31, v36
	v_lshlrev_b64 v[36:37], 12, v[36:37]
	v_lshl_add_u64 v[36:37], v[8:9], 0, v[36:37]
	global_load_dword v33, v[36:37], off nt
.LBB0_2223:
	v_mov_b32_e32 v35, 0
	s_and_b64 vcc, exec, s[0:1]
	v_mov_b32_e32 v36, 0
	s_cbranch_vccnz .LBB0_2225
	v_or_b32_e32 v36, 44, v10
	v_ashrrev_i32_e32 v37, 31, v36
	v_lshlrev_b64 v[36:37], 12, v[36:37]
	v_lshl_add_u64 v[36:37], v[8:9], 0, v[36:37]
	global_load_dword v36, v[36:37], off nt
.LBB0_2225:
	s_and_b64 vcc, exec, s[0:1]
	s_cbranch_vccnz .LBB0_2227
	v_or_b32_e32 v38, 46, v10
	v_ashrrev_i32_e32 v39, 31, v38
	v_lshlrev_b64 v[38:39], 12, v[38:39]
	v_lshl_add_u64 v[38:39], v[8:9], 0, v[38:39]
	global_load_dword v35, v[38:39], off nt
.LBB0_2227:
	v_mov_b32_e32 v37, 0
	s_and_b64 vcc, exec, s[0:1]
	v_mov_b32_e32 v38, 0
	s_cbranch_vccnz .LBB0_2229
	v_or_b32_e32 v38, 48, v10
	v_ashrrev_i32_e32 v39, 31, v38
	v_lshlrev_b64 v[38:39], 12, v[38:39]
	v_lshl_add_u64 v[38:39], v[8:9], 0, v[38:39]
	global_load_dword v38, v[38:39], off nt
.LBB0_2229:
	s_and_b64 vcc, exec, s[0:1]
	s_cbranch_vccnz .LBB0_2231
	v_or_b32_e32 v40, 50, v10
	v_ashrrev_i32_e32 v41, 31, v40
	v_lshlrev_b64 v[40:41], 12, v[40:41]
	v_lshl_add_u64 v[40:41], v[8:9], 0, v[40:41]
	global_load_dword v37, v[40:41], off nt
.LBB0_2231:
	v_mov_b32_e32 v39, 0
	s_and_b64 vcc, exec, s[0:1]
	v_mov_b32_e32 v40, 0
	s_cbranch_vccnz .LBB0_2233
	v_or_b32_e32 v40, 52, v10
	v_ashrrev_i32_e32 v41, 31, v40
	v_lshlrev_b64 v[40:41], 12, v[40:41]
	v_lshl_add_u64 v[40:41], v[8:9], 0, v[40:41]
	global_load_dword v40, v[40:41], off nt
.LBB0_2233:
	s_and_b64 vcc, exec, s[0:1]
	s_cbranch_vccnz .LBB0_2235
	v_or_b32_e32 v42, 54, v10
	v_ashrrev_i32_e32 v43, 31, v42
	v_lshlrev_b64 v[42:43], 12, v[42:43]
	v_lshl_add_u64 v[42:43], v[8:9], 0, v[42:43]
	global_load_dword v39, v[42:43], off nt
.LBB0_2235:
	v_mov_b32_e32 v41, 0
	s_and_b64 vcc, exec, s[0:1]
	v_mov_b32_e32 v42, 0
	s_cbranch_vccnz .LBB0_2237
	v_or_b32_e32 v42, 56, v10
	v_ashrrev_i32_e32 v43, 31, v42
	v_lshlrev_b64 v[42:43], 12, v[42:43]
	v_lshl_add_u64 v[42:43], v[8:9], 0, v[42:43]
	global_load_dword v42, v[42:43], off nt
.LBB0_2237:
	s_and_b64 vcc, exec, s[0:1]
	s_cbranch_vccnz .LBB0_2239
	v_or_b32_e32 v44, 58, v10
	v_ashrrev_i32_e32 v45, 31, v44
	v_lshlrev_b64 v[44:45], 12, v[44:45]
	v_lshl_add_u64 v[44:45], v[8:9], 0, v[44:45]
	global_load_dword v41, v[44:45], off nt
.LBB0_2239:
	v_mov_b32_e32 v43, 0
	s_and_b64 vcc, exec, s[0:1]
	v_mov_b32_e32 v44, 0
	s_cbranch_vccnz .LBB0_2241
	v_or_b32_e32 v44, 60, v10
	v_ashrrev_i32_e32 v45, 31, v44
	v_lshlrev_b64 v[44:45], 12, v[44:45]
	v_lshl_add_u64 v[44:45], v[8:9], 0, v[44:45]
	global_load_dword v44, v[44:45], off nt
.LBB0_2241:
	s_and_b64 vcc, exec, s[0:1]
	s_cbranch_vccnz .LBB0_2178
	v_or_b32_e32 v52, 62, v10
	v_ashrrev_i32_e32 v53, 31, v52
	v_lshlrev_b64 v[52:53], 12, v[52:53]
	v_lshl_add_u64 v[8:9], v[8:9], 0, v[52:53]
	global_load_dword v43, v[8:9], off nt
	s_branch .LBB0_2178

.LBB0_2246:
	v_ashrrev_i32_e32 v6, 31, v12
	v_lshrrev_b32_e32 v6, 27, v6
	v_add_u32_e32 v6, v12, v6
	v_ashrrev_i32_e32 v7, 5, v6
	v_lshlrev_b32_e32 v6, 6, v7
	v_lshlrev_b32_e32 v7, 10, v7
	v_add_u32_e32 v8, v48, v13
	v_sub_u32_e32 v8, v8, v7
	v_readlane_b32 s36, v238, 37
	v_ashrrev_i32_e32 v9, 31, v8
	v_readlane_b32 s40, v238, 41
	v_readlane_b32 s41, v238, 42
	v_or_b32_e32 v10, v6, v1
	v_mov_b32_e32 v14, 0
	v_lshl_add_u64 v[8:9], v[8:9], 2, s[40:41]
	s_and_b64 vcc, exec, s[0:1]
	v_mov_b32_e32 v11, 0
	v_readlane_b32 s37, v238, 38
	v_readlane_b32 s38, v238, 39
	v_readlane_b32 s39, v238, 40
	v_readlane_b32 s42, v238, 43
	v_readlane_b32 s43, v238, 44
	v_readlane_b32 s44, v238, 45
	v_readlane_b32 s45, v238, 46
	v_readlane_b32 s46, v238, 47
	v_readlane_b32 s47, v238, 48
	v_readlane_b32 s48, v238, 49
	v_readlane_b32 s49, v238, 50
	v_readlane_b32 s50, v238, 51
	v_readlane_b32 s51, v238, 52
	s_cbranch_vccnz .LBB0_2248
	v_ashrrev_i32_e32 v11, 31, v10
	v_lshlrev_b64 v[16:17], 12, v[10:11]
	v_lshl_add_u64 v[16:17], v[8:9], 0, v[16:17]
	global_load_dword v11, v[16:17], off nt

.LBB0_2313:
	v_ashrrev_i32_e32 v6, 31, v12
	v_lshrrev_b32_e32 v6, 27, v6
	v_add_u32_e32 v6, v12, v6
	v_ashrrev_i32_e32 v7, 5, v6
	v_lshlrev_b32_e32 v6, 6, v7
	v_lshlrev_b32_e32 v7, 10, v7
	v_add_u32_e32 v8, v48, v13
	v_sub_u32_e32 v8, v8, v7
	v_readlane_b32 s36, v238, 37
	v_ashrrev_i32_e32 v9, 31, v8
	v_readlane_b32 s42, v238, 43
	v_readlane_b32 s43, v238, 44
	v_or_b32_e32 v10, v6, v1
	v_mov_b32_e32 v14, 0
	v_lshl_add_u64 v[8:9], v[8:9], 2, s[42:43]
	s_and_b64 vcc, exec, s[0:1]
	v_mov_b32_e32 v11, 0
	v_readlane_b32 s37, v238, 38
	v_readlane_b32 s38, v238, 39
	v_readlane_b32 s39, v238, 40
	v_readlane_b32 s40, v238, 41
	v_readlane_b32 s41, v238, 42
	v_readlane_b32 s44, v238, 45
	v_readlane_b32 s45, v238, 46
	v_readlane_b32 s46, v238, 47
	v_readlane_b32 s47, v238, 48
	v_readlane_b32 s48, v238, 49
	v_readlane_b32 s49, v238, 50
	v_readlane_b32 s50, v238, 51
	v_readlane_b32 s51, v238, 52
	s_cbranch_vccnz .LBB0_2315
	v_ashrrev_i32_e32 v11, 31, v10
	v_lshlrev_b64 v[16:17], 12, v[10:11]
	v_lshl_add_u64 v[16:17], v[8:9], 0, v[16:17]
	global_load_dword v11, v[16:17], off nt

.LBB0_2380:
	v_mul_hi_i32 v8, v7, s16
	v_lshrrev_b32_e32 v9, 31, v8
	v_ashrrev_i32_e32 v8, 5, v8
	v_add_u32_e32 v9, v8, v9
	v_mul_lo_u32 v56, v9, s17
	v_add_u32_e32 v12, v51, v56
	v_mad_u64_u32 v[10:11], s[8:9], v9, s18, v[6:7]
	v_lshlrev_b32_e32 v8, 6, v9
	v_and_b32_e32 v9, 0xffffff80, v10
	v_and_b32_e32 v10, 0x60, v12
	v_or3_b32 v10, v10, v9, v48
	v_and_b32_e32 v9, 4, v7
	v_cmp_eq_u32_e32 vcc, 0, v9
	v_ashrrev_i32_e32 v11, 31, v10
	v_or_b32_e32 v28, v8, v1
	v_cndmask_b32_e32 v13, v52, v53, vcc
	v_cndmask_b32_e32 v12, v54, v55, vcc
	v_lshl_add_u64 v[32:33], v[10:11], 2, v[12:13]
	v_cmp_ne_u64_e32 vcc, 0, v[12:13]
	v_mov_b32_e32 v11, 0
	v_mov_b32_e32 v10, 0
	s_and_saveexec_b64 s[8:9], vcc
	s_cbranch_execz .LBB0_2382
	v_mad_i64_i32 v[12:13], s[22:23], v28, s19, v[32:33]
	global_load_dword v10, v[12:13], off nt
.LBB0_2382:
	s_or_b64 exec, exec, s[8:9]
	s_and_saveexec_b64 s[8:9], vcc
	s_cbranch_execz .LBB0_2384
	v_or_b32_e32 v9, 2, v28
	v_mad_i64_i32 v[12:13], s[22:23], v9, s19, v[32:33]
	global_load_dword v11, v[12:13], off nt
.LBB0_2384:
	s_or_b64 exec, exec, s[8:9]
	v_mov_b32_e32 v13, 0
	v_mov_b32_e32 v12, 0
	s_and_saveexec_b64 s[8:9], vcc
	s_cbranch_execz .LBB0_2386
	v_or_b32_e32 v9, 4, v28
	v_mad_i64_i32 v[14:15], s[22:23], v9, s19, v[32:33]
	global_load_dword v12, v[14:15], off nt
.LBB0_2386:
	s_or_b64 exec, exec, s[8:9]
	s_and_saveexec_b64 s[8:9], vcc
	s_cbranch_execz .LBB0_2388
	v_or_b32_e32 v9, 6, v28
	v_mad_i64_i32 v[14:15], s[22:23], v9, s19, v[32:33]
	global_load_dword v13, v[14:15], off nt
.LBB0_2388:
	s_or_b64 exec, exec, s[8:9]
	v_mov_b32_e32 v15, 0
	v_mov_b32_e32 v14, 0
	s_and_saveexec_b64 s[8:9], vcc
	s_cbranch_execz .LBB0_2390
	v_or_b32_e32 v9, 8, v28
	v_mad_i64_i32 v[16:17], s[22:23], v9, s19, v[32:33]
	global_load_dword v14, v[16:17], off nt
.LBB0_2390:
	s_or_b64 exec, exec, s[8:9]
	s_and_saveexec_b64 s[8:9], vcc
	s_cbranch_execz .LBB0_2392
	v_or_b32_e32 v9, 10, v28
	v_mad_i64_i32 v[16:17], s[22:23], v9, s19, v[32:33]
	global_load_dword v15, v[16:17], off nt
.LBB0_2392:
	s_or_b64 exec, exec, s[8:9]
	v_mov_b32_e32 v17, 0
	v_mov_b32_e32 v16, 0
	s_and_saveexec_b64 s[8:9], vcc
	s_cbranch_execz .LBB0_2394
	v_or_b32_e32 v9, 12, v28
	v_mad_i64_i32 v[18:19], s[22:23], v9, s19, v[32:33]
	global_load_dword v16, v[18:19], off nt
.LBB0_2394:
	s_or_b64 exec, exec, s[8:9]
	s_and_saveexec_b64 s[8:9], vcc
	s_cbranch_execz .LBB0_2396
	v_or_b32_e32 v9, 14, v28
	v_mad_i64_i32 v[18:19], s[22:23], v9, s19, v[32:33]
	global_load_dword v17, v[18:19], off nt
.LBB0_2396:
	s_or_b64 exec, exec, s[8:9]
	v_mov_b32_e32 v19, 0
	v_mov_b32_e32 v18, 0
	s_and_saveexec_b64 s[8:9], vcc
	s_cbranch_execz .LBB0_2398
	v_or_b32_e32 v9, 16, v28
	v_mad_i64_i32 v[20:21], s[22:23], v9, s19, v[32:33]
	global_load_dword v18, v[20:21], off nt
.LBB0_2398:
	s_or_b64 exec, exec, s[8:9]
	s_and_saveexec_b64 s[8:9], vcc
	s_cbranch_execz .LBB0_2400
	v_or_b32_e32 v9, 18, v28
	v_mad_i64_i32 v[20:21], s[22:23], v9, s19, v[32:33]
	global_load_dword v19, v[20:21], off nt
.LBB0_2400:
	s_or_b64 exec, exec, s[8:9]
	v_mov_b32_e32 v21, 0
	v_mov_b32_e32 v20, 0
	s_and_saveexec_b64 s[8:9], vcc
	s_cbranch_execz .LBB0_2402
	v_or_b32_e32 v9, 20, v28
	v_mad_i64_i32 v[22:23], s[22:23], v9, s19, v[32:33]
	global_load_dword v20, v[22:23], off nt
.LBB0_2402:
	s_or_b64 exec, exec, s[8:9]
	s_and_saveexec_b64 s[8:9], vcc
	s_cbranch_execz .LBB0_2404
	v_or_b32_e32 v9, 22, v28
	v_mad_i64_i32 v[22:23], s[22:23], v9, s19, v[32:33]
	global_load_dword v21, v[22:23], off nt
.LBB0_2404:
	s_or_b64 exec, exec, s[8:9]
	v_mov_b32_e32 v23, 0
	v_mov_b32_e32 v22, 0
	s_and_saveexec_b64 s[8:9], vcc
	s_cbranch_execz .LBB0_2406
	v_or_b32_e32 v9, 24, v28
	v_mad_i64_i32 v[24:25], s[22:23], v9, s19, v[32:33]
	global_load_dword v22, v[24:25], off nt
.LBB0_2406:
	s_or_b64 exec, exec, s[8:9]
	s_and_saveexec_b64 s[8:9], vcc
	s_cbranch_execz .LBB0_2408
	v_or_b32_e32 v9, 26, v28
	v_mad_i64_i32 v[24:25], s[22:23], v9, s19, v[32:33]
	global_load_dword v23, v[24:25], off nt
.LBB0_2408:
	s_or_b64 exec, exec, s[8:9]
	v_mov_b32_e32 v25, 0
	v_mov_b32_e32 v24, 0
	s_and_saveexec_b64 s[8:9], vcc
	s_cbranch_execz .LBB0_2410
	v_or_b32_e32 v9, 28, v28
	v_mad_i64_i32 v[26:27], s[22:23], v9, s19, v[32:33]
	global_load_dword v24, v[26:27], off nt
.LBB0_2410:
	s_or_b64 exec, exec, s[8:9]
	s_and_saveexec_b64 s[8:9], vcc
	s_cbranch_execz .LBB0_2412
	v_or_b32_e32 v9, 30, v28
	v_mad_i64_i32 v[26:27], s[22:23], v9, s19, v[32:33]
	global_load_dword v25, v[26:27], off nt
.LBB0_2412:
	s_or_b64 exec, exec, s[8:9]
	v_mov_b32_e32 v27, 0
	v_mov_b32_e32 v26, 0
	s_and_saveexec_b64 s[8:9], vcc
	s_cbranch_execz .LBB0_2414
	v_or_b32_e32 v9, 32, v28
	v_mad_i64_i32 v[30:31], s[22:23], v9, s19, v[32:33]
	global_load_dword v26, v[30:31], off nt
.LBB0_2414:
	s_or_b64 exec, exec, s[8:9]
	s_and_saveexec_b64 s[8:9], vcc
	s_cbranch_execz .LBB0_2416
	v_or_b32_e32 v9, 34, v28
	v_mad_i64_i32 v[30:31], s[22:23], v9, s19, v[32:33]
	global_load_dword v27, v[30:31], off nt
.LBB0_2416:
	s_or_b64 exec, exec, s[8:9]
	v_mov_b32_e32 v31, 0
	v_mov_b32_e32 v30, 0
	s_and_saveexec_b64 s[8:9], vcc
	s_cbranch_execz .LBB0_2418
	v_or_b32_e32 v9, 36, v28
	v_mad_i64_i32 v[34:35], s[22:23], v9, s19, v[32:33]
	global_load_dword v30, v[34:35], off nt
.LBB0_2418:
	s_or_b64 exec, exec, s[8:9]
	s_and_saveexec_b64 s[8:9], vcc
	s_cbranch_execz .LBB0_2420
	v_or_b32_e32 v9, 38, v28
	v_mad_i64_i32 v[34:35], s[22:23], v9, s19, v[32:33]
	global_load_dword v31, v[34:35], off nt
.LBB0_2420:
	s_or_b64 exec, exec, s[8:9]
	v_mov_b32_e32 v35, 0
	v_mov_b32_e32 v34, 0
	s_and_saveexec_b64 s[8:9], vcc
	s_cbranch_execz .LBB0_2422
	v_or_b32_e32 v9, 40, v28
	v_mad_i64_i32 v[36:37], s[22:23], v9, s19, v[32:33]
	global_load_dword v34, v[36:37], off nt
.LBB0_2422:
	s_or_b64 exec, exec, s[8:9]
	s_and_saveexec_b64 s[8:9], vcc
	s_cbranch_execz .LBB0_2424
	v_or_b32_e32 v9, 42, v28
	v_mad_i64_i32 v[36:37], s[22:23], v9, s19, v[32:33]
	global_load_dword v35, v[36:37], off nt
.LBB0_2424:
	s_or_b64 exec, exec, s[8:9]
	v_mov_b32_e32 v37, 0
	v_mov_b32_e32 v36, 0
	s_and_saveexec_b64 s[8:9], vcc
	s_cbranch_execz .LBB0_2426
	v_or_b32_e32 v9, 44, v28
	v_mad_i64_i32 v[38:39], s[22:23], v9, s19, v[32:33]
	global_load_dword v36, v[38:39], off nt
.LBB0_2426:
	s_or_b64 exec, exec, s[8:9]
	s_and_saveexec_b64 s[8:9], vcc
	s_cbranch_execz .LBB0_2428
	v_or_b32_e32 v9, 46, v28
	v_mad_i64_i32 v[38:39], s[22:23], v9, s19, v[32:33]
	global_load_dword v37, v[38:39], off nt
.LBB0_2428:
	s_or_b64 exec, exec, s[8:9]
	v_mov_b32_e32 v39, 0
	v_mov_b32_e32 v38, 0
	s_and_saveexec_b64 s[8:9], vcc
	s_cbranch_execz .LBB0_2430
	v_or_b32_e32 v9, 48, v28
	v_mad_i64_i32 v[40:41], s[22:23], v9, s19, v[32:33]
	global_load_dword v38, v[40:41], off nt
.LBB0_2430:
	s_or_b64 exec, exec, s[8:9]
	s_and_saveexec_b64 s[8:9], vcc
	s_cbranch_execz .LBB0_2432
	v_or_b32_e32 v9, 50, v28
	v_mad_i64_i32 v[40:41], s[22:23], v9, s19, v[32:33]
	global_load_dword v39, v[40:41], off nt
.LBB0_2432:
	s_or_b64 exec, exec, s[8:9]
	v_mov_b32_e32 v41, 0
	v_mov_b32_e32 v40, 0
	s_and_saveexec_b64 s[8:9], vcc
	s_cbranch_execz .LBB0_2434
	v_or_b32_e32 v9, 52, v28
	v_mad_i64_i32 v[42:43], s[22:23], v9, s19, v[32:33]
	global_load_dword v40, v[42:43], off nt
.LBB0_2434:
	s_or_b64 exec, exec, s[8:9]
	s_and_saveexec_b64 s[8:9], vcc
	s_cbranch_execz .LBB0_2436
	v_or_b32_e32 v9, 54, v28
	v_mad_i64_i32 v[42:43], s[22:23], v9, s19, v[32:33]
	global_load_dword v41, v[42:43], off nt
.LBB0_2436:
	s_or_b64 exec, exec, s[8:9]
	v_mov_b32_e32 v43, 0
	v_mov_b32_e32 v42, 0
	s_and_saveexec_b64 s[8:9], vcc
	s_cbranch_execz .LBB0_2438
	v_or_b32_e32 v9, 56, v28
	v_mad_i64_i32 v[44:45], s[22:23], v9, s19, v[32:33]
	global_load_dword v42, v[44:45], off nt
.LBB0_2438:
	s_or_b64 exec, exec, s[8:9]
	s_and_saveexec_b64 s[8:9], vcc
	s_cbranch_execz .LBB0_2440
	v_or_b32_e32 v9, 58, v28
	v_mad_i64_i32 v[44:45], s[22:23], v9, s19, v[32:33]
	global_load_dword v43, v[44:45], off nt

.LBB0_2443:
	v_or_b32_e32 v9, 60, v28
	v_mad_i64_i32 v[58:59], s[22:23], v9, s19, v[32:33]
	global_load_dword v44, v[58:59], off nt
	s_or_b64 exec, exec, s[8:9]
	s_and_saveexec_b64 s[8:9], vcc
	s_cbranch_execz .LBB0_2442
.LBB0_2444:
	v_or_b32_e32 v9, 62, v28
	v_mad_i64_i32 v[32:33], s[22:23], v9, s19, v[32:33]
	global_load_dword v45, v[32:33], off nt
	s_or_b64 exec, exec, s[8:9]
	s_andn2_b64 vcc, exec, s[6:7]
	s_cbranch_vccnz .LBB0_2379
.LBB0_2445:
	v_readlane_b32 s36, v238, 37
	v_ashrrev_i32_e32 v29, 31, v28
	v_readlane_b32 s44, v238, 45
	v_readlane_b32 s45, v238, 46
	v_readlane_b32 s37, v238, 38
	v_readlane_b32 s38, v238, 39
	v_lshl_add_u64 v[28:29], v[28:29], 2, s[44:45]
	global_load_dword v32, v[28:29], off nt
	global_load_dword v33, v[28:29], off offset:8
	global_load_dword v58, v[28:29], off offset:16
	global_load_dword v59, v[28:29], off offset:24
	global_load_dword v60, v[28:29], off offset:32
	global_load_dword v61, v[28:29], off offset:40
	global_load_dword v62, v[28:29], off offset:48
	global_load_dword v63, v[28:29], off offset:56
	global_load_dword v64, v[28:29], off offset:64
	global_load_dword v65, v[28:29], off offset:72
	global_load_dword v66, v[28:29], off offset:80
	global_load_dword v67, v[28:29], off offset:88
	global_load_dword v68, v[28:29], off offset:96
	global_load_dword v69, v[28:29], off offset:104
	global_load_dword v70, v[28:29], off offset:112
	global_load_dword v71, v[28:29], off offset:120
	global_load_dword v72, v[28:29], off offset:128
	global_load_dword v73, v[28:29], off offset:136
	global_load_dword v74, v[28:29], off offset:144
	global_load_dword v75, v[28:29], off offset:152
	global_load_dword v76, v[28:29], off offset:160
	global_load_dword v77, v[28:29], off offset:168
	global_load_dword v78, v[28:29], off offset:176
	global_load_dword v79, v[28:29], off offset:184
	global_load_dword v80, v[28:29], off offset:192
	global_load_dword v81, v[28:29], off offset:200
	global_load_dword v82, v[28:29], off offset:208
	global_load_dword v83, v[28:29], off offset:216
	global_load_dword v84, v[28:29], off offset:224
	global_load_dword v85, v[28:29], off offset:232
	global_load_dword v86, v[28:29], off offset:240
	global_load_dword v87, v[28:29], off offset:248
	v_readlane_b32 s39, v238, 40
	v_readlane_b32 s40, v238, 41
	v_readlane_b32 s41, v238, 42
	v_readlane_b32 s42, v238, 43
	v_readlane_b32 s43, v238, 44
	v_readlane_b32 s46, v238, 47
	v_readlane_b32 s47, v238, 48
	v_readlane_b32 s48, v238, 49
	v_readlane_b32 s49, v238, 50
	v_readlane_b32 s50, v238, 51
	v_readlane_b32 s51, v238, 52
	s_waitcnt vmcnt(30)
	v_pk_mul_f32 v[10:11], v[10:11], v[32:33]
	s_waitcnt vmcnt(28)
	v_pk_mul_f32 v[12:13], v[12:13], v[58:59]
	s_waitcnt vmcnt(26)
	v_pk_mul_f32 v[14:15], v[14:15], v[60:61]
	s_waitcnt vmcnt(24)
	v_pk_mul_f32 v[16:17], v[16:17], v[62:63]
	s_waitcnt vmcnt(22)
	v_pk_mul_f32 v[18:19], v[18:19], v[64:65]
	s_waitcnt vmcnt(20)
	v_pk_mul_f32 v[20:21], v[20:21], v[66:67]
	s_waitcnt vmcnt(18)
	v_pk_mul_f32 v[22:23], v[22:23], v[68:69]
	s_waitcnt vmcnt(16)
	v_pk_mul_f32 v[24:25], v[24:25], v[70:71]
	s_waitcnt vmcnt(14)
	v_pk_mul_f32 v[26:27], v[26:27], v[72:73]
	s_waitcnt vmcnt(12)
	v_pk_mul_f32 v[30:31], v[30:31], v[74:75]
	s_waitcnt vmcnt(10)
	v_pk_mul_f32 v[34:35], v[34:35], v[76:77]
	s_waitcnt vmcnt(8)
	v_pk_mul_f32 v[36:37], v[36:37], v[78:79]
	s_waitcnt vmcnt(6)
	v_pk_mul_f32 v[38:39], v[38:39], v[80:81]
	s_waitcnt vmcnt(4)
	v_pk_mul_f32 v[40:41], v[40:41], v[82:83]
	s_waitcnt vmcnt(2)
	v_pk_mul_f32 v[42:43], v[42:43], v[84:85]
	s_waitcnt vmcnt(0)
	v_pk_mul_f32 v[44:45], v[44:45], v[86:87]
	s_branch .LBB0_2379
.LBB0_2446:
	s_or_b64 exec, exec, s[0:1]
	s_mul_hi_u32 s0, s11, 0x1d00
	s_mul_i32 s0, s0, s10
	s_sub_i32 s0, 0x1d00, s0
	s_sub_i32 s1, s0, s10
	s_cmp_ge_u32 s0, s10
	s_cselect_b32 s0, s1, s0
	s_sub_i32 s1, s0, s10
	s_cmp_ge_u32 s0, s10
	s_cselect_b32 s0, s1, s0
	v_subrev_u32_e32 v4, s0, v50
	v_sub_u32_e32 v6, 0, v4
	v_ashrrev_i32_e32 v5, 31, v4
	v_max_i32_e32 v4, v4, v6
	v_mul_hi_u32 v6, v4, s11
	v_mul_lo_u32 v6, v6, s10
	v_sub_u32_e32 v4, v4, v6
	v_subrev_u32_e32 v6, s10, v4
	v_cmp_le_u32_e32 vcc, s10, v4
	s_movk_i32 s0, 0x580
	s_nop 0
	v_cndmask_b32_e32 v4, v4, v6, vcc
	v_subrev_u32_e32 v6, s10, v4
	v_cmp_le_u32_e32 vcc, s10, v4
	s_nop 1
	v_cndmask_b32_e32 v4, v4, v6, vcc
	v_xor_b32_e32 v4, v4, v5
	v_sub_u32_e32 v5, v4, v5
	v_cmp_gt_i32_e32 vcc, s0, v5
	s_and_saveexec_b64 s[4:5], vcc
	s_cbranch_execz .LBB0_2513
	v_readlane_b32 s36, v238, 37
	v_readlane_b32 s50, v238, 51
	v_readlane_b32 s51, v238, 52
	s_mov_b64 s[0:1], 0x3400000
	s_cmp_lg_u64 s[50:51], 0
	v_lshl_add_u64 v[2:3], v[2:3], 0, s[0:1]
	s_cselect_b64 s[0:1], -1, 0
	s_mov_b32 s8, 0x16000
	v_mul_lo_u32 v4, v5, s8
	s_movk_i32 s8, 0xb00
	v_cndmask_b32_e64 v6, 0, 1, s[0:1]
	s_mov_b64 s[6:7], 0
	v_mad_u32_u24 v4, v49, s8, v4
	s_mul_i32 s8, s3, 0x16000
	v_lshl_or_b32 v12, v5, 5, v48
	s_lshl_b32 s9, s3, 5
	v_cmp_ne_u32_e64 s[0:1], 1, v6
	s_mov_b32 s10, 0xffd40000
	s_movk_i32 s11, 0x57f
	v_readlane_b32 s37, v238, 38
	v_readlane_b32 s38, v238, 39
	v_readlane_b32 s39, v238, 40
	v_readlane_b32 s40, v238, 41
	v_readlane_b32 s41, v238, 42
	v_readlane_b32 s42, v238, 43
	v_readlane_b32 s43, v238, 44
	v_readlane_b32 s44, v238, 45
	v_readlane_b32 s45, v238, 46
	v_readlane_b32 s46, v238, 47
	v_readlane_b32 s47, v238, 48
	v_readlane_b32 s48, v238, 49
	v_readlane_b32 s49, v238, 50
	s_branch .LBB0_2449
.LBB0_2448:
	s_waitcnt vmcnt(0)
	ds_write2_b32 v46, v11, v7 offset1:66
	ds_write2_b32 v46, v15, v14 offset0:132 offset1:198
	v_add_u32_e32 v7, 0x400, v46
	ds_write2_b32 v7, v17, v16 offset0:8 offset1:74
	ds_write2_b32 v7, v19, v18 offset0:140 offset1:206
	v_add_u32_e32 v7, 0x800, v46
	ds_write2_b32 v7, v21, v20 offset0:16 offset1:82
	ds_write2_b32 v7, v23, v22 offset0:148 offset1:214
	v_add_u32_e32 v7, 0xc00, v46
	ds_write2_b32 v7, v25, v24 offset0:24 offset1:90
	ds_write2_b32 v7, v27, v26 offset0:156 offset1:222
	v_add_u32_e32 v7, 0x1000, v46
	ds_write2_b32 v7, v29, v28 offset0:32 offset1:98
	ds_write2_b32 v7, v31, v30 offset0:164 offset1:230
	v_add_u32_e32 v7, 0x1400, v46
	ds_write2_b32 v7, v33, v32 offset0:40 offset1:106
	ds_write2_b32 v7, v35, v34 offset0:172 offset1:238
	v_add_u32_e32 v7, 0x1800, v46
	ds_write2_b32 v7, v37, v36 offset0:48 offset1:114
	ds_write2_b32 v7, v39, v38 offset0:180 offset1:246
	v_add_u32_e32 v7, 0x1c00, v46
	ds_write2_b32 v7, v41, v40 offset0:56 offset1:122
	ds_write2_b32 v7, v43, v42 offset0:188 offset1:254
	s_waitcnt lgkmcnt(0)
	ds_read2_b32 v[10:11], v47 offset0:33 offset1:41
	ds_read2_b32 v[14:15], v47 offset1:8
	ds_read2_b32 v[16:17], v47 offset0:66 offset1:74
	ds_read2_b32 v[18:19], v47 offset0:99 offset1:107
	ds_read2_b32 v[20:21], v47 offset0:132 offset1:140
	ds_read2_b32 v[22:23], v47 offset0:165 offset1:173
	ds_read2_b32 v[24:25], v47 offset0:198 offset1:206
	ds_read2_b32 v[26:27], v47 offset0:231 offset1:239
	v_ashrrev_i32_e32 v7, 31, v6
	v_mad_u64_u32 v[30:31], s[12:13], v13, s10, v[4:5]
	v_lshl_add_u64 v[28:29], v[6:7], 1, v[2:3]
	v_ashrrev_i32_e32 v31, 31, v30
	s_waitcnt lgkmcnt(6)
	v_cvt_pk_bf16_f32 v6, v14, v10
	s_waitcnt lgkmcnt(4)
	v_cvt_pk_bf16_f32 v7, v16, v18
	s_waitcnt lgkmcnt(2)
	v_cvt_pk_bf16_f32 v8, v20, v22
	s_waitcnt lgkmcnt(0)
	v_cvt_pk_bf16_f32 v9, v24, v26
	v_lshl_add_u64 v[32:33], v[30:31], 1, v[28:29]
	global_store_dwordx4 v[32:33], v[6:9], off
	v_add_u32_e32 v10, 0x5800, v30
	v_add_u32_e32 v5, s3, v5
	v_cvt_pk_bf16_f32 v6, v15, v11
	v_cvt_pk_bf16_f32 v7, v17, v19
	v_cvt_pk_bf16_f32 v8, v21, v23
	v_cvt_pk_bf16_f32 v9, v25, v27
	ds_read2_b32 v[14:15], v47 offset0:49 offset1:57
	ds_read2_b32 v[16:17], v47 offset0:16 offset1:24
	ds_read2_b32 v[18:19], v47 offset0:82 offset1:90
	ds_read2_b32 v[20:21], v47 offset0:115 offset1:123
	ds_read2_b32 v[22:23], v47 offset0:148 offset1:156
	ds_read2_b32 v[24:25], v47 offset0:181 offset1:189
	ds_read2_b32 v[26:27], v47 offset0:214 offset1:222
	ds_read2_b32 v[32:33], v47 offset0:247 offset1:255
	v_ashrrev_i32_e32 v11, 31, v10
	v_lshl_add_u64 v[10:11], v[10:11], 1, v[28:29]
	global_store_dwordx4 v[10:11], v[6:9], off
	v_add_u32_e32 v10, 0xb000, v30
	v_ashrrev_i32_e32 v11, 31, v10
	s_waitcnt lgkmcnt(6)
	v_cvt_pk_bf16_f32 v6, v16, v14
	s_waitcnt lgkmcnt(4)
	v_cvt_pk_bf16_f32 v7, v18, v20
	s_waitcnt lgkmcnt(2)
	v_cvt_pk_bf16_f32 v8, v22, v24
	s_waitcnt lgkmcnt(0)
	v_cvt_pk_bf16_f32 v9, v26, v32
	v_lshl_add_u64 v[10:11], v[10:11], 1, v[28:29]
	global_store_dwordx4 v[10:11], v[6:9], off
	v_add_u32_e32 v10, 0x10800, v30
	v_ashrrev_i32_e32 v11, 31, v10
	v_cvt_pk_bf16_f32 v6, v17, v15
	v_cvt_pk_bf16_f32 v7, v19, v21
	v_cvt_pk_bf16_f32 v8, v23, v25
	v_cvt_pk_bf16_f32 v9, v27, v33
	v_lshl_add_u64 v[10:11], v[10:11], 1, v[28:29]
	global_store_dwordx4 v[10:11], v[6:9], off
	s_waitcnt lgkmcnt(0)
	v_cmp_lt_i32_e32 vcc, s11, v5
	v_add_u32_e32 v4, s8, v4
	s_or_b64 s[6:7], vcc, s[6:7]
	v_add_u32_e32 v12, s9, v12
	s_andn2_b64 exec, exec, s[6:7]
	s_cbranch_execz .LBB0_2513
.LBB0_2449:
	v_ashrrev_i32_e32 v6, 31, v5
	v_lshrrev_b32_e32 v6, 27, v6
	v_add_u32_e32 v6, v5, v6
	v_ashrrev_i32_e32 v13, 5, v6
	v_lshlrev_b32_e32 v7, 10, v13
	v_sub_u32_e32 v8, v12, v7
	v_readlane_b32 s36, v238, 37
	v_lshlrev_b32_e32 v6, 6, v13
	v_ashrrev_i32_e32 v9, 31, v8
	v_readlane_b32 s50, v238, 51
	v_readlane_b32 s51, v238, 52
	v_or_b32_e32 v10, v6, v1
	v_mov_b32_e32 v7, 0
	v_lshl_add_u64 v[8:9], v[8:9], 2, s[50:51]
	s_and_b64 vcc, exec, s[0:1]
	v_mov_b32_e32 v11, 0
	v_readlane_b32 s37, v238, 38
	v_readlane_b32 s38, v238, 39
	v_readlane_b32 s39, v238, 40
	v_readlane_b32 s40, v238, 41
	v_readlane_b32 s41, v238, 42
	v_readlane_b32 s42, v238, 43
	v_readlane_b32 s43, v238, 44
	v_readlane_b32 s44, v238, 45
	v_readlane_b32 s45, v238, 46
	v_readlane_b32 s46, v238, 47
	v_readlane_b32 s47, v238, 48
	v_readlane_b32 s48, v238, 49
	v_readlane_b32 s49, v238, 50
	s_cbranch_vccnz .LBB0_2451
	v_ashrrev_i32_e32 v11, 31, v10
	v_lshlrev_b64 v[14:15], 12, v[10:11]
	v_lshl_add_u64 v[14:15], v[8:9], 0, v[14:15]
	global_load_dword v11, v[14:15], off nt

.LBB0_2501:
	v_mov_b32_e32 v38, 0
	s_and_b64 vcc, exec, s[0:1]
	v_mov_b32_e32 v39, 0
	s_cbranch_vccnz .LBB0_2503
	v_or_b32_e32 v40, 52, v10
	v_ashrrev_i32_e32 v41, 31, v40
	v_lshlrev_b64 v[40:41], 12, v[40:41]
	v_lshl_add_u64 v[40:41], v[8:9], 0, v[40:41]
	global_load_dword v39, v[40:41], off nt
.LBB0_2503:
	s_and_b64 vcc, exec, s[0:1]
	s_cbranch_vccnz .LBB0_2505
	v_or_b32_e32 v40, 54, v10
	v_ashrrev_i32_e32 v41, 31, v40
	v_lshlrev_b64 v[40:41], 12, v[40:41]
	v_lshl_add_u64 v[40:41], v[8:9], 0, v[40:41]
	global_load_dword v38, v[40:41], off nt
.LBB0_2505:
	v_mov_b32_e32 v40, 0
	s_and_b64 vcc, exec, s[0:1]
	v_mov_b32_e32 v41, 0
	s_cbranch_vccnz .LBB0_2507
	v_or_b32_e32 v42, 56, v10
	v_ashrrev_i32_e32 v43, 31, v42
	v_lshlrev_b64 v[42:43], 12, v[42:43]
	v_lshl_add_u64 v[42:43], v[8:9], 0, v[42:43]
	global_load_dword v41, v[42:43], off nt

.LBB0_2511:
	s_and_b64 vcc, exec, s[0:1]
	s_cbranch_vccnz .LBB0_2448
	v_or_b32_e32 v44, 62, v10
	v_ashrrev_i32_e32 v45, 31, v44
	v_lshlrev_b64 v[44:45], 12, v[44:45]
	v_lshl_add_u64 v[8:9], v[8:9], 0, v[44:45]
	global_load_dword v42, v[8:9], off nt
	s_branch .LBB0_2448
.LBB0_2513:
	s_or_b64 exec, exec, s[4:5]
	s_mov_b64 s[0:1], 0
